# SSD mixer: next-chunk raw loads issued back to back with one counted wait before the bf16 pair packing (was 14 interleaved waits)
# baseline (speedup 1.0000x reference)
.LBB0_588:
	s_waitcnt lgkmcnt(0)
	v_sub_f32_e32 v36, v161, v36
	v_mul_f32_e32 v36, 0x3fb8aa3b, v36
	v_and_b32_e32 v41, 0xffff0000, v208
	v_lshlrev_b32_e32 v40, 16, v208
	v_and_b32_e32 v47, 0xffff0000, v192
	v_lshlrev_b32_e32 v46, 16, v192
	v_exp_f32_e32 v225, v36
	v_pk_mul_f32 v[36:37], v[90:91], v[40:41]
	v_pk_mul_f32 v[48:49], v[86:87], v[46:47]
	v_mov_b32_e32 v46, v47
	v_mov_b32_e32 v47, v41
	v_mul_f32_e32 v45, v91, v40
	v_pk_fma_f32 v[46:47], v[94:95], v[46:47], v[48:49]
	v_mov_b32_e32 v44, v37
	v_pk_add_f32 v[44:45], v[44:45], v[46:47]
	v_and_b32_e32 v47, 0xffff0000, v209
	v_or_b32_e32 v38, s58, v224
	v_mul_f32_e32 v37, v90, v47
	v_lshlrev_b32_e32 v39, 2, v38
	v_pk_add_f32 v[36:37], v[36:37], v[44:45]
	ds_bpermute_b32 v38, v39, v1
	ds_bpermute_b32 v42, v39, v225
	v_or_b32_e32 v39, s48, v224
	v_pk_add_f32 v[36:37], v[84:85], v[36:37]
	v_lshlrev_b32_e32 v43, 2, v39
	v_mul_f32_e32 v39, 0xbfb8aa3b, v36
	v_exp_f32_e32 v44, v39
	v_mul_f32_e32 v39, 0xbfb8aa3b, v37
	v_exp_f32_e32 v45, v39
	ds_bpermute_b32 v39, v43, v1
	v_add_f32_e32 v44, 1.0, v44
	v_rcp_f32_e32 v44, v44
	v_add_f32_e32 v45, 1.0, v45
	v_rcp_f32_e32 v45, v45
	ds_bpermute_b32 v43, v43, v225
	s_mul_i32 s27, s59, 0x900
	v_pk_mul_f32 v[48:49], v[102:103], v[40:41]
	v_pk_mul_f32 v[36:37], v[36:37], v[44:45]
	v_add_u32_e32 v44, s27, v151
	v_cvt_pk_bf16_f32 v41, v36, s0
	ds_write_b16 v44, v41 offset:18432
	s_mul_i32 s27, s48, 0x90
	v_or_b32_e32 v41, s49, v224
	v_lshlrev_b32_e32 v46, 16, v209
	s_waitcnt lgkmcnt(2)
	v_pk_mul_f32 v[38:39], v[36:37], v[38:39]
	v_cvt_pk_bf16_f32 v36, v37, s0
	v_add_u32_e32 v250, s27, v151
	v_lshlrev_b32_e32 v41, 2, v41
	ds_write_b16 v250, v36 offset:18432
	s_waitcnt lgkmcnt(2)
	v_pk_mul_f32 v[36:37], v[38:39], v[42:43]
	v_pk_mul_f32 v[42:43], v[90:91], v[46:47]
	ds_bpermute_b32 v44, v41, v1
	ds_bpermute_b32 v50, v41, v225
	v_mul_f32_e32 v41, v86, v40
	v_mul_f32_e32 v53, v94, v47
	v_mov_b32_e32 v52, v48
	v_mov_b32_e32 v40, v49
	v_mul_f32_e32 v55, v91, v46
	v_pk_add_f32 v[40:41], v[52:53], v[40:41]
	v_mov_b32_e32 v54, v43
	v_lshlrev_b32_e32 v48, 16, v210
	v_pk_add_f32 v[40:41], v[54:55], v[40:41]
	v_mul_f32_e32 v43, v90, v48
	v_pk_add_f32 v[40:41], v[42:43], v[40:41]
	v_or_b32_e32 v45, s96, v224
	v_pk_add_f32 v[40:41], v[84:85], v[40:41]
	v_lshlrev_b32_e32 v49, 2, v45
	v_mul_f32_e32 v42, 0xbfb8aa3b, v40
	v_mul_f32_e32 v43, 0xbfb8aa3b, v41
	v_exp_f32_e32 v42, v42
	v_exp_f32_e32 v43, v43
	ds_bpermute_b32 v45, v49, v1
	ds_bpermute_b32 v51, v49, v225
	v_add_f32_e32 v42, 1.0, v42
	v_add_f32_e32 v43, 1.0, v43
	v_rcp_f32_e32 v42, v42
	v_rcp_f32_e32 v43, v43
	v_and_b32_e32 v49, 0xffff0000, v210
	v_mov_b32_e32 v54, v48
	v_mov_b32_e32 v55, v46
	v_pk_mul_f32 v[40:41], v[40:41], v[42:43]
	v_mul_f32_e32 v56, v102, v48
	v_cvt_pk_bf16_f32 v42, v40, s0
	ds_write_b16 v250, v42 offset:18576
	s_waitcnt lgkmcnt(2)
	v_pk_mul_f32 v[42:43], v[40:41], v[44:45]
	v_cvt_pk_bf16_f32 v40, v41, s0
	ds_write_b16 v250, v40 offset:18720
	s_waitcnt lgkmcnt(2)
	v_pk_mul_f32 v[40:41], v[42:43], v[50:51]
	v_pk_mul_f32 v[44:45], v[104:105], v[48:49]
	v_or_b32_e32 v50, s97, v224
	v_pk_fma_f32 v[54:55], v[102:103], v[54:55], v[56:57] op_sel_hi:[1,1,0]
	v_lshlrev_b32_e32 v51, 2, v50
	v_mov_b32_e32 v54, v44
	v_mul_f32_e32 v44, v103, v47
	ds_bpermute_b32 v50, v51, v1
	ds_bpermute_b32 v52, v51, v225
	v_mul_f32_e32 v51, v91, v49
	v_pk_fma_f32 v[46:47], v[102:103], v[46:47], v[44:45] op_sel_hi:[1,1,0]
	v_mov_b32_e32 v56, v45
	v_mov_b32_e32 v47, v51
	v_pk_add_f32 v[46:47], v[54:55], v[46:47]
	v_lshlrev_b32_e32 v54, 16, v211
	v_mul_f32_e32 v57, v90, v54
	v_pk_add_f32 v[44:45], v[46:47], v[56:57]
	v_or_b32_e32 v53, s12, v224
	v_pk_add_f32 v[44:45], v[84:85], v[44:45]
	v_lshlrev_b32_e32 v53, 2, v53
	v_mul_f32_e32 v46, 0xbfb8aa3b, v44
	v_mul_f32_e32 v47, 0xbfb8aa3b, v45
	v_exp_f32_e32 v46, v46
	v_exp_f32_e32 v47, v47
	ds_bpermute_b32 v51, v53, v1
	v_pk_mul_f32 v[56:57], v[106:107], v[48:49]
	v_add_f32_e32 v46, 1.0, v46
	v_add_f32_e32 v47, 1.0, v47
	v_rcp_f32_e32 v46, v46
	v_rcp_f32_e32 v47, v47
	v_and_b32_e32 v55, 0xffff0000, v211
	ds_bpermute_b32 v53, v53, v225
	v_mul_f32_e32 v59, v86, v49
	v_pk_mul_f32 v[44:45], v[44:45], v[46:47]
	v_mul_f32_e32 v61, v94, v54
	v_cvt_pk_bf16_f32 v46, v44, s0
	ds_write_b16 v250, v46 offset:18864
	s_waitcnt lgkmcnt(2)
	v_pk_mul_f32 v[46:47], v[44:45], v[50:51]
	v_pk_mul_f32 v[50:51], v[104:105], v[54:55]
	v_mov_b32_e32 v58, v56
	v_mov_b32_e32 v60, v57
	v_mul_f32_e32 v63, v91, v55
	v_pk_add_f32 v[56:57], v[58:59], v[60:61]
	v_mov_b32_e32 v62, v50
	v_lshlrev_b32_e32 v50, 16, v212
	v_pk_add_f32 v[56:57], v[56:57], v[62:63]
	v_mul_f32_e32 v59, v90, v50
	v_mov_b32_e32 v58, v51
	v_pk_add_f32 v[56:57], v[56:57], v[58:59]
	v_cvt_pk_bf16_f32 v44, v45, s0
	v_or_b32_e32 v49, s14, v224
	v_pk_add_f32 v[56:57], v[84:85], v[56:57]
	ds_write_b16 v250, v44 offset:19008
	s_waitcnt lgkmcnt(2)
	v_pk_mul_f32 v[44:45], v[46:47], v[52:53]
	v_lshlrev_b32_e32 v53, 2, v49
	v_mul_f32_e32 v49, 0xbfb8aa3b, v56
	v_exp_f32_e32 v51, v49
	v_mul_f32_e32 v49, 0xbfb8aa3b, v57
	v_exp_f32_e32 v59, v49
	v_or_b32_e32 v48, s13, v224
	v_add_f32_e32 v51, 1.0, v51
	v_lshlrev_b32_e32 v52, 2, v48
	v_rcp_f32_e32 v58, v51
	v_add_f32_e32 v51, 1.0, v59
	ds_bpermute_b32 v48, v52, v1
	ds_bpermute_b32 v49, v53, v1
	v_rcp_f32_e32 v59, v51
	ds_bpermute_b32 v52, v52, v225
	ds_bpermute_b32 v53, v53, v225
	v_pk_mul_f32 v[60:61], v[106:107], v[54:55]
	v_pk_mul_f32 v[56:57], v[56:57], v[58:59]
	v_and_b32_e32 v51, 0xffff0000, v212
	s_waitcnt lgkmcnt(2)
	v_pk_mul_f32 v[58:59], v[56:57], v[48:49]
	v_cvt_pk_bf16_f32 v48, v57, s0
	ds_write_b16 v250, v48 offset:19296
	s_waitcnt lgkmcnt(1)
	v_pk_mul_f32 v[48:49], v[58:59], v[52:53]
	v_pk_mul_f32 v[52:53], v[104:105], v[50:51]
	v_mul_f32_e32 v63, v86, v55
	v_mul_f32_e32 v135, v94, v50
	v_mov_b32_e32 v62, v60
	v_mov_b32_e32 v134, v61
	v_mul_f32_e32 v227, v91, v51
	v_pk_add_f32 v[60:61], v[62:63], v[134:135]
	v_mov_b32_e32 v226, v52
	v_lshlrev_b32_e32 v52, 16, v213
	v_pk_add_f32 v[60:61], v[60:61], v[226:227]
	v_mul_f32_e32 v63, v90, v52
	v_mov_b32_e32 v62, v53
	v_pk_add_f32 v[60:61], v[60:61], v[62:63]
	v_or_b32_e32 v55, s16, v224
	v_pk_add_f32 v[60:61], v[84:85], v[60:61]
	v_lshlrev_b32_e32 v57, 2, v55
	v_mul_f32_e32 v53, 0xbfb8aa3b, v60
	v_exp_f32_e32 v53, v53
	v_mul_f32_e32 v55, 0xbfb8aa3b, v61
	v_exp_f32_e32 v63, v55
	v_cvt_pk_bf16_f32 v54, v56, s0
	ds_write_b16 v250, v54 offset:19152
	v_or_b32_e32 v54, s15, v224
	v_add_f32_e32 v53, 1.0, v53
	v_lshlrev_b32_e32 v56, 2, v54
	v_rcp_f32_e32 v62, v53
	v_add_f32_e32 v53, 1.0, v63
	ds_bpermute_b32 v54, v56, v1
	ds_bpermute_b32 v55, v57, v1
	v_rcp_f32_e32 v63, v53
	ds_bpermute_b32 v56, v56, v225
	ds_bpermute_b32 v57, v57, v225
	v_pk_mul_f32 v[134:135], v[106:107], v[50:51]
	v_pk_mul_f32 v[60:61], v[60:61], v[62:63]
	v_and_b32_e32 v53, 0xffff0000, v213
	v_cvt_pk_bf16_f32 v50, v60, s0
	s_waitcnt lgkmcnt(2)
	v_pk_mul_f32 v[54:55], v[60:61], v[54:55]
	ds_write_b16 v250, v50 offset:19440
	v_cvt_pk_bf16_f32 v50, v61, s0
	s_waitcnt lgkmcnt(1)
	v_pk_mul_f32 v[60:61], v[54:55], v[56:57]
	v_pk_mul_f32 v[56:57], v[104:105], v[52:53]
	v_mul_f32_e32 v227, v86, v51
	v_mul_f32_e32 v229, v94, v52
	v_mov_b32_e32 v226, v134
	v_mov_b32_e32 v228, v135
	v_mul_f32_e32 v243, v91, v53
	v_pk_add_f32 v[134:135], v[226:227], v[228:229]
	v_mov_b32_e32 v242, v56
	v_lshlrev_b32_e32 v56, 16, v214
	v_pk_add_f32 v[134:135], v[134:135], v[242:243]
	v_mul_f32_e32 v227, v90, v56
	v_mov_b32_e32 v226, v57
	v_pk_add_f32 v[134:135], v[134:135], v[226:227]
	v_or_b32_e32 v51, s18, v224
	v_pk_add_f32 v[134:135], v[84:85], v[134:135]
	v_lshlrev_b32_e32 v63, 2, v51
	v_mul_f32_e32 v51, 0xbfb8aa3b, v134
	v_exp_f32_e32 v57, v51
	v_mul_f32_e32 v51, 0xbfb8aa3b, v135
	v_exp_f32_e32 v227, v51
	ds_write_b16 v250, v50 offset:19584
	v_or_b32_e32 v50, s17, v224
	v_add_f32_e32 v57, 1.0, v57
	v_lshlrev_b32_e32 v62, 2, v50
	v_rcp_f32_e32 v226, v57
	v_add_f32_e32 v57, 1.0, v227
	ds_bpermute_b32 v50, v62, v1
	ds_bpermute_b32 v51, v63, v1
	v_rcp_f32_e32 v227, v57
	v_pk_mul_f32 v[228:229], v[106:107], v[52:53]
	v_and_b32_e32 v57, 0xffff0000, v214
	v_mul_f32_e32 v243, v86, v53
	v_pk_mul_f32 v[134:135], v[134:135], v[226:227]
	v_mul_f32_e32 v245, v94, v56
	s_waitcnt lgkmcnt(0)
	v_pk_mul_f32 v[226:227], v[134:135], v[50:51]
	v_cvt_pk_bf16_f32 v50, v135, s0
	ds_write_b16 v250, v50 offset:19872
	v_pk_mul_f32 v[50:51], v[104:105], v[56:57]
	v_mov_b32_e32 v242, v228
	v_mov_b32_e32 v244, v229
	v_mul_f32_e32 v247, v91, v57
	v_pk_add_f32 v[228:229], v[242:243], v[244:245]
	v_mov_b32_e32 v246, v50
	v_lshlrev_b32_e32 v50, 16, v215
	v_pk_add_f32 v[228:229], v[228:229], v[246:247]
	v_mul_f32_e32 v243, v90, v50
	v_mov_b32_e32 v242, v51
	v_pk_add_f32 v[228:229], v[228:229], v[242:243]
	v_or_b32_e32 v53, s20, v224
	v_pk_add_f32 v[228:229], v[84:85], v[228:229]
	v_lshlrev_b32_e32 v135, 2, v53
	v_mul_f32_e32 v51, 0xbfb8aa3b, v228
	v_exp_f32_e32 v51, v51
	v_mul_f32_e32 v53, 0xbfb8aa3b, v229
	v_exp_f32_e32 v243, v53
	v_cvt_pk_bf16_f32 v52, v134, s0
	ds_write_b16 v250, v52 offset:19728
	v_or_b32_e32 v52, s19, v224
	v_add_f32_e32 v51, 1.0, v51
	v_lshlrev_b32_e32 v134, 2, v52
	v_rcp_f32_e32 v242, v51
	v_add_f32_e32 v51, 1.0, v243
	ds_bpermute_b32 v52, v134, v1
	ds_bpermute_b32 v53, v135, v1
	v_rcp_f32_e32 v243, v51
	v_pk_mul_f32 v[244:245], v[106:107], v[56:57]
	v_and_b32_e32 v51, 0xffff0000, v215
	v_mul_f32_e32 v247, v94, v50
	v_pk_mul_f32 v[228:229], v[228:229], v[242:243]
	v_mov_b32_e32 v246, v245
	s_waitcnt lgkmcnt(0)
	v_pk_mul_f32 v[242:243], v[228:229], v[52:53]
	v_cvt_pk_bf16_f32 v52, v229, s0
	v_cvt_pk_bf16_f32 v56, v228, s0
	ds_write_b16 v250, v52 offset:20160
	v_pk_mul_f32 v[52:53], v[104:105], v[50:51]
	v_mul_f32_e32 v229, v86, v57
	v_lshlrev_b32_e32 v50, 16, v204
	v_mov_b32_e32 v228, v244
	v_mul_f32_e32 v51, v91, v51
	v_mul_f32_e32 v249, v90, v50
	v_pk_add_f32 v[228:229], v[228:229], v[246:247]
	v_mov_b32_e32 v50, v52
	v_pk_add_f32 v[50:51], v[228:229], v[50:51]
	v_mov_b32_e32 v248, v53
	v_pk_add_f32 v[50:51], v[50:51], v[248:249]
	ds_write_b16 v250, v56 offset:20016
	v_pk_add_f32 v[50:51], v[84:85], v[50:51]
	v_or_b32_e32 v56, s21, v224
	v_mul_f32_e32 v52, 0xbfb8aa3b, v50
	v_exp_f32_e32 v53, v52
	v_mul_f32_e32 v52, 0xbfb8aa3b, v51
	v_exp_f32_e32 v57, v52
	v_lshlrev_b32_e32 v251, 2, v56
	v_add_f32_e32 v53, 1.0, v53
	v_rcp_f32_e32 v228, v53
	v_add_f32_e32 v53, 1.0, v57
	v_rcp_f32_e32 v229, v53
	v_or_b32_e32 v53, s26, v224
	v_lshlrev_b32_e32 v53, 2, v53
	ds_bpermute_b32 v56, v251, v1
	ds_bpermute_b32 v57, v53, v1
	ds_bpermute_b32 v62, v62, v225
	ds_bpermute_b32 v63, v63, v225
	ds_bpermute_b32 v134, v134, v225
	ds_bpermute_b32 v135, v135, v225
	ds_bpermute_b32 v52, v251, v225
	ds_bpermute_b32 v53, v53, v225
	v_pk_mul_f32 v[50:51], v[50:51], v[228:229]
	s_waitcnt lgkmcnt(4)
	v_pk_mul_f32 v[62:63], v[226:227], v[62:63]
	v_cvt_pk_bf16_f32 v1, v50, s0
	v_pk_mul_f32 v[228:229], v[50:51], v[56:57]
	s_waitcnt lgkmcnt(2)
	v_pk_mul_f32 v[134:135], v[242:243], v[134:135]
	ds_write_b16 v250, v1 offset:20304
	v_cvt_pk_bf16_f32 v1, v51, s0
	s_waitcnt lgkmcnt(1)
	v_pk_mul_f32 v[244:245], v[228:229], v[52:53]
	v_cvt_pk_bf16_f32 v50, v38, v39
	v_cvt_pk_bf16_f32 v51, v42, v43
	v_cvt_pk_bf16_f32 v52, v46, v47
	v_cvt_pk_bf16_f32 v53, v58, v59
	v_cvt_pk_bf16_f32 v36, v36, v37
	v_cvt_pk_bf16_f32 v37, v40, v41
	v_cvt_pk_bf16_f32 v38, v44, v45
	v_cvt_pk_bf16_f32 v39, v48, v49
	ds_write_b16 v250, v1 offset:20448
	v_cvt_pk_bf16_f32 v54, v54, v55
	v_cvt_pk_bf16_f32 v55, v226, v227
	v_cvt_pk_bf16_f32 v56, v242, v243
	v_cvt_pk_bf16_f32 v57, v228, v229
	ds_write_b128 v182, v[50:53] offset:53248
	ds_write_b128 v182, v[54:57] offset:53264
	v_cvt_pk_bf16_f32 v40, v60, v61
	v_cvt_pk_bf16_f32 v41, v62, v63
	v_cvt_pk_bf16_f32 v42, v134, v135
	v_cvt_pk_bf16_f32 v43, v244, v245
	ds_write_b128 v182, v[36:39] offset:62464
	ds_write_b128 v182, v[40:43] offset:62480
	v_cvt_pk_bf16_f32 v36, v28, v29
	v_cvt_pk_bf16_f32 v37, v30, v31
	v_cvt_pk_bf16_f32 v44, v32, v33
	v_cvt_pk_bf16_f32 v45, v34, v35
	v_add_u32_e32 v1, 0x6800, v137
	s_add_i32 s60, s60, 1
	v_cvt_pk_bf16_f32 v38, v24, v25
	v_cvt_pk_bf16_f32 v39, v26, v27
	ds_write2_b64 v1, v[36:37], v[44:45] offset0:128 offset1:132
	v_cvt_pk_bf16_f32 v36, v16, v17
	v_cvt_pk_bf16_f32 v37, v18, v19
	v_add_u32_e32 v1, 0x7800, v137
	s_cmp_ge_u32 s60, s61
	v_cvt_pk_bf16_f32 v40, v20, v21
	v_cvt_pk_bf16_f32 v41, v22, v23
	ds_write2_b64 v1, v[38:39], v[36:37] offset0:160 offset1:164
	v_cvt_pk_bf16_f32 v36, v12, v13
	v_cvt_pk_bf16_f32 v37, v14, v15
	v_add_u32_e32 v1, 0x8800, v137
	s_cselect_b64 s[54:55], -1, 0
	v_cvt_pk_bf16_f32 v42, v4, v5
	v_cvt_pk_bf16_f32 v43, v6, v7
	ds_write2_b64 v1, v[40:41], v[36:37] offset0:192 offset1:196
	v_cvt_pk_bf16_f32 v36, v8, v9
	v_cvt_pk_bf16_f32 v37, v10, v11
	v_add_u32_e32 v1, 0x9800, v137
	s_and_b64 vcc, exec, s[54:55]
	ds_write2_b64 v1, v[42:43], v[36:37] offset0:224 offset1:228
	s_waitcnt lgkmcnt(0)
	s_barrier
	s_cbranch_vccnz .LBB0_590
	v_lshl_add_u64 v[36:37], s[72:73], 0, v[74:75]
	v_add_co_u32_e32 v38, vcc, 0x361c000, v36
	s_mov_b32 s27, 0x361c000
	s_nop 0
	v_addc_co_u32_e32 v39, vcc, 0, v37, vcc
	global_load_ushort v192, v[38:39], off offset:1536
	global_load_ushort v1, v[38:39], off offset:2048
	global_load_ushort v147, v[38:39], off offset:2560
	v_add_co_u32_e32 v38, vcc, 0x361e000, v36
	s_nop 1
	v_addc_co_u32_e32 v39, vcc, 0, v37, vcc
	v_add_co_u32_e32 v36, vcc, 0x3620000, v36
	global_load_ushort v148, v[38:39], off offset:2048
	global_load_ushort v40, v[38:39], off offset:2560
	global_load_ushort v149, v[38:39], off offset:3072
	v_addc_co_u32_e32 v37, vcc, 0, v37, vcc
	global_load_ushort v41, v[36:37], off offset:2560
	global_load_ushort v42, v[36:37], off offset:3072
	global_load_ushort v150, v[36:37], off offset:3584
	v_lshl_add_u64 v[36:37], s[72:73], 0, v[80:81]
	global_load_ushort v43, v[36:37], off offset:-512
	global_load_ushort v44, v[36:37], off
	global_load_ushort v178, v[36:37], off offset:512
	v_lshl_add_u64 v[36:37], s[72:73], 0, v[116:117]
	v_add_co_u32_e32 v38, vcc, 0x3602000, v36
	s_nop 0
	s_nop 0
	v_addc_co_u32_e32 v39, vcc, 0, v37, vcc
	global_load_ushort v45, v[38:39], off offset:3584
	v_add_co_u32_e32 v38, vcc, 0x3603000, v36
	s_nop 1
	v_addc_co_u32_e32 v39, vcc, 0, v37, vcc
	global_load_ushort v46, v[38:39], off
	global_load_ushort v179, v[38:39], off offset:512
	v_add_co_u32_e32 v38, vcc, 0x3605000, v36
	s_nop 1
	v_addc_co_u32_e32 v39, vcc, 0, v37, vcc
	global_load_ushort v47, v[38:39], off
	global_load_ushort v48, v[38:39], off offset:512
	global_load_ushort v184, v[38:39], off offset:1024
	v_add_co_u32_e32 v38, vcc, 0x3607000, v36
	s_nop 0
	s_nop 0
	v_addc_co_u32_e32 v39, vcc, 0, v37, vcc
	global_load_ushort v49, v[38:39], off offset:512
	global_load_ushort v50, v[38:39], off offset:1024
	global_load_ushort v183, v[38:39], off offset:1536
	v_add_co_u32_e32 v38, vcc, 0x3609000, v36
	s_nop 0
	s_nop 0
	v_addc_co_u32_e32 v39, vcc, 0, v37, vcc
	global_load_ushort v51, v[38:39], off offset:1024
	global_load_ushort v52, v[38:39], off offset:1536
	global_load_ushort v185, v[38:39], off offset:2048
	v_add_co_u32_e32 v38, vcc, 0x360b000, v36
	s_nop 0
	s_nop 0
	v_addc_co_u32_e32 v39, vcc, 0, v37, vcc
	global_load_ushort v53, v[38:39], off offset:1536
	global_load_ushort v54, v[38:39], off offset:2048
	global_load_ushort v186, v[38:39], off offset:2560
	v_add_co_u32_e32 v38, vcc, 0x360d000, v36
	s_nop 0
	s_nop 0
	v_addc_co_u32_e32 v39, vcc, 0, v37, vcc
	global_load_ushort v55, v[38:39], off offset:2048
	global_load_ushort v56, v[38:39], off offset:2560
	global_load_ushort v191, v[38:39], off offset:3072
	v_add_co_u32_e32 v38, vcc, 0x360f000, v36
	s_nop 0
	s_nop 0
	v_addc_co_u32_e32 v39, vcc, 0, v37, vcc
	global_load_ushort v57, v[38:39], off offset:2560
	global_load_ushort v58, v[38:39], off offset:3072
	global_load_ushort v193, v[38:39], off offset:3584
	v_add_co_u32_e32 v38, vcc, 0x3611000, v36
	s_nop 0
	s_nop 0
	v_addc_co_u32_e32 v39, vcc, 0, v37, vcc
	global_load_ushort v59, v[38:39], off offset:3072
	global_load_ushort v60, v[38:39], off offset:3584
	v_add_co_u32_e32 v38, vcc, 0x3612000, v36
	s_nop 0
	s_nop 0
	v_addc_co_u32_e32 v39, vcc, 0, v37, vcc
	global_load_ushort v197, v[38:39], off
	v_add_co_u32_e32 v38, vcc, 0x3613000, v36
	s_nop 0
	s_nop 0
	v_addc_co_u32_e32 v39, vcc, 0, v37, vcc
	global_load_ushort v61, v[38:39], off offset:3584
	v_add_co_u32_e32 v38, vcc, 0x3614000, v36
	s_nop 1
	v_addc_co_u32_e32 v39, vcc, 0, v37, vcc
	global_load_ushort v62, v[38:39], off
	global_load_ushort v198, v[38:39], off offset:512
	v_add_co_u32_e32 v38, vcc, 0x3616000, v36
	s_nop 1
	v_addc_co_u32_e32 v39, vcc, 0, v37, vcc
	global_load_ushort v63, v[38:39], off
	global_load_ushort v134, v[38:39], off offset:512
	global_load_ushort v199, v[38:39], off offset:1024
	v_add_co_u32_e32 v38, vcc, 0x3618000, v36
	s_nop 0
	s_nop 0
	v_addc_co_u32_e32 v39, vcc, 0, v37, vcc
	global_load_ushort v135, v[38:39], off offset:512
	global_load_ushort v222, v[38:39], off offset:1024
	global_load_ushort v200, v[38:39], off offset:1536
	v_add_co_u32_e32 v38, vcc, 0x361a000, v36
	s_nop 0
	s_nop 0
	v_addc_co_u32_e32 v39, vcc, 0, v37, vcc
	global_load_ushort v207, v[38:39], off offset:1024
	global_load_ushort v223, v[38:39], off offset:1536
	global_load_ushort v201, v[38:39], off offset:2048
	v_add_co_u32_e32 v38, vcc, s27, v36
	s_mov_b32 s27, 0x361e000
	s_nop 0
	v_addc_co_u32_e32 v39, vcc, 0, v37, vcc
	global_load_ushort v215, v[38:39], off offset:1536
	global_load_ushort v225, v[38:39], off offset:2048
	global_load_ushort v202, v[38:39], off offset:2560
	v_add_co_u32_e32 v38, vcc, s27, v36
	s_mov_b32 s27, 0x3620000
	s_nop 0
	v_addc_co_u32_e32 v39, vcc, 0, v37, vcc
	v_add_co_u32_e32 v36, vcc, s27, v36
	global_load_ushort v216, v[38:39], off offset:2048
	global_load_ushort v226, v[38:39], off offset:2560
	global_load_ushort v203, v[38:39], off offset:3072
	v_addc_co_u32_e32 v37, vcc, 0, v37, vcc
	global_load_ushort v204, v[36:37], off offset:2560
	global_load_ushort v206, v[36:37], off offset:3072
	global_load_ushort v205, v[36:37], off offset:3584
	v_lshl_add_u64 v[36:37], s[72:73], 0, v[114:115]
	global_load_ushort v177, v[36:37], off
	s_waitcnt vmcnt(5)
	v_perm_b32 v208, v41, v43, s71
	v_perm_b32 v209, v45, v47, s71
	v_perm_b32 v217, v46, v48, s71
	v_perm_b32 v210, v51, v49, s71
	v_perm_b32 v218, v50, v52, s71
	v_perm_b32 v211, v55, v53, s71
	v_perm_b32 v219, v54, v56, s71
	v_perm_b32 v212, v59, v57, s71
	v_perm_b32 v220, v58, v60, s71
	v_perm_b32 v213, v63, v61, s71
	v_perm_b32 v221, v62, v134, s71
	v_perm_b32 v214, v207, v135, s71
	v_perm_b32 v207, v40, v1, s71
	v_perm_b32 v222, v222, v223, s71
	v_perm_b32 v215, v216, v215, s71
	v_perm_b32 v216, v42, v44, s71
	v_perm_b32 v223, v225, v226, s71
